# slc loop: next-tile index computed on the scalar unit (mask in SGPR) instead of 64-bit VALU ops; on top of v38
# baseline (speedup 1.0000x reference)
.LBB0_1970:
	s_lshl_b32 s6, s3, 8
	s_waitcnt lgkmcnt(0)
	s_add_i32 s8, s6, 0
	s_add_i32 s8, s8, 0x10000
	v_lshl_add_u32 v146, v143, 2, s8
	s_barrier
	s_and_saveexec_b64 s[6:7], s[4:5]
	v_mul_f32_e32 v66, v134, v66
	ds_write_b32 v146, v66
	s_or_b64 exec, exec, s[6:7]
	s_add_i32 s7, s54, 0xfffffe00
	s_lshr_b32 s6, s57, 1
	s_ashr_i32 s7, s7, 6
	s_cmpk_lt_u32 s55, 0x2f0
	s_cselect_b32 s7, s7, 0
	s_lshl_b64 s[10:11], 2, s6
	s_lshl_b64 s[12:13], -1, s7
	s_lshl_b32 s7, s58, 1
	v_readlane_b32 s9, v254, 55
	s_add_u32 s55, s9, s7
	v_readlane_b32 s9, v254, 56
	v_max_f32_e32 v0, v0, v0
	v_max_f32_e32 v66, v135, v135
	s_addc_u32 s57, s9, 0
	v_readlane_b32 s9, v254, 57
	s_waitcnt lgkmcnt(0)
	v_add_u32_e32 v149, s8, v180
	v_max_f32_e32 v0, v0, v66
	s_add_u32 s58, s9, s7
	v_readlane_b32 s7, v254, 58
	ds_read_b128 v[66:69], v149
	ds_read_b128 v[70:73], v149 offset:32
	ds_read_b128 v[74:77], v149 offset:64
	ds_read_b128 v[78:81], v149 offset:96
	s_addc_u32 s59, s7, 0
	s_add_u32 s10, s10, -1
	s_addc_u32 s11, s11, -1
	s_lshl_b32 s7, s3, 13
	v_fma_f32 v0, v191, v0, v190
	s_add_i32 s7, s7, 0
	v_add_f32_e32 v153, 0x3d4ccccd, v0
	v_lshl_add_u32 v0, v155, 2, s7
	s_and_b64 s[18:19], s[12:13], s[10:11]
	v_add_u32_e32 v148, 0x14000, v0
	s_waitcnt lgkmcnt(0)
	v_mul_f32_e32 v0, v50, v66
	v_mul_f32_e32 v50, v51, v67
	v_cvt_pk_bf16_f32 v0, v0, v50
	ds_write_b32 v148, v0
	v_mul_f32_e32 v0, v34, v66
	v_mul_f32_e32 v34, v35, v67
	v_cvt_pk_bf16_f32 v0, v0, v34
	ds_write_b32 v148, v0 offset:2048
	v_mul_f32_e32 v0, v52, v68
	v_mul_f32_e32 v34, v53, v69
	v_cvt_pk_bf16_f32 v0, v0, v34
	ds_write_b32 v148, v0 offset:256
	v_mul_f32_e32 v0, v36, v68
	v_mul_f32_e32 v34, v37, v69
	v_cvt_pk_bf16_f32 v0, v0, v34
	ds_write_b32 v148, v0 offset:2304
	v_mul_f32_e32 v0, v54, v70
	v_mul_f32_e32 v34, v55, v71
	v_cvt_pk_bf16_f32 v0, v0, v34
	ds_write_b32 v148, v0 offset:512
	v_mul_f32_e32 v0, v38, v70
	v_mul_f32_e32 v34, v39, v71
	v_cvt_pk_bf16_f32 v0, v0, v34
	ds_write_b32 v148, v0 offset:2560
	v_mul_f32_e32 v0, v56, v72
	v_mul_f32_e32 v34, v57, v73
	v_cvt_pk_bf16_f32 v0, v0, v34
	ds_write_b32 v148, v0 offset:768
	v_mul_f32_e32 v0, v40, v72
	v_mul_f32_e32 v34, v41, v73
	v_cvt_pk_bf16_f32 v0, v0, v34
	ds_write_b32 v148, v0 offset:2816
	v_mul_f32_e32 v0, v58, v74
	v_mul_f32_e32 v34, v59, v75
	v_cvt_pk_bf16_f32 v0, v0, v34
	ds_write_b32 v148, v0 offset:1024
	v_mul_f32_e32 v0, v42, v74
	v_mul_f32_e32 v34, v43, v75
	v_cvt_pk_bf16_f32 v0, v0, v34
	ds_write_b32 v148, v0 offset:3072
	v_mul_f32_e32 v0, v60, v76
	v_mul_f32_e32 v34, v61, v77
	v_cvt_pk_bf16_f32 v0, v0, v34
	ds_write_b32 v148, v0 offset:1280
	v_mul_f32_e32 v0, v44, v76
	v_mul_f32_e32 v34, v45, v77
	v_cvt_pk_bf16_f32 v0, v0, v34
	ds_write_b32 v148, v0 offset:3328
	v_mul_f32_e32 v0, v62, v78
	v_mul_f32_e32 v34, v63, v79
	v_cvt_pk_bf16_f32 v0, v0, v34
	ds_write_b32 v148, v0 offset:1536
	v_mul_f32_e32 v0, v46, v78
	v_mul_f32_e32 v34, v47, v79
	v_cvt_pk_bf16_f32 v0, v0, v34
	ds_write_b32 v148, v0 offset:3584
	v_mul_f32_e32 v0, v64, v80
	v_mul_f32_e32 v34, v65, v81
	v_cvt_pk_bf16_f32 v0, v0, v34
	ds_write_b32 v148, v0 offset:1792
	v_mul_f32_e32 v0, v48, v80
	v_mul_f32_e32 v34, v49, v81
	v_cvt_pk_bf16_f32 v0, v0, v34
	ds_write_b32 v148, v0 offset:3840
	v_mul_f32_e32 v0, v18, v66
	v_mul_f32_e32 v18, v19, v67
	v_cvt_pk_bf16_f32 v0, v0, v18
	ds_write_b32 v148, v0 offset:4096
	v_mul_f32_e32 v0, v2, v66
	v_mul_f32_e32 v2, v3, v67
	v_cvt_pk_bf16_f32 v0, v0, v2
	ds_write_b32 v148, v0 offset:6144
	v_mul_f32_e32 v0, v20, v68
	v_mul_f32_e32 v2, v21, v69
	v_cvt_pk_bf16_f32 v0, v0, v2
	ds_write_b32 v148, v0 offset:4352
	v_mul_f32_e32 v0, v4, v68
	v_mul_f32_e32 v2, v5, v69
	v_cvt_pk_bf16_f32 v0, v0, v2
	ds_write_b32 v148, v0 offset:6400
	v_mul_f32_e32 v0, v22, v70
	v_mul_f32_e32 v2, v23, v71
	v_cvt_pk_bf16_f32 v0, v0, v2
	ds_write_b32 v148, v0 offset:4608
	v_mul_f32_e32 v0, v6, v70
	v_mul_f32_e32 v2, v7, v71
	v_cvt_pk_bf16_f32 v0, v0, v2
	ds_write_b32 v148, v0 offset:6656
	v_mul_f32_e32 v0, v24, v72
	v_mul_f32_e32 v2, v25, v73
	v_cvt_pk_bf16_f32 v0, v0, v2
	ds_write_b32 v148, v0 offset:4864
	v_mul_f32_e32 v0, v8, v72
	v_mul_f32_e32 v2, v9, v73
	v_cvt_pk_bf16_f32 v0, v0, v2
	ds_write_b32 v148, v0 offset:6912
	v_mul_f32_e32 v0, v26, v74
	v_mul_f32_e32 v2, v27, v75
	v_cvt_pk_bf16_f32 v0, v0, v2
	ds_write_b32 v148, v0 offset:5120
	v_mul_f32_e32 v0, v10, v74
	v_mul_f32_e32 v2, v11, v75
	v_cvt_pk_bf16_f32 v0, v0, v2
	ds_write_b32 v148, v0 offset:7168
	v_mul_f32_e32 v0, v28, v76
	v_mul_f32_e32 v2, v29, v77
	v_cvt_pk_bf16_f32 v0, v0, v2
	ds_write_b32 v148, v0 offset:5376
	v_mul_f32_e32 v0, v12, v76
	v_mul_f32_e32 v2, v13, v77
	v_cvt_pk_bf16_f32 v0, v0, v2
	ds_write_b32 v148, v0 offset:7424
	v_mul_f32_e32 v0, v30, v78
	v_mul_f32_e32 v2, v31, v79
	v_cvt_pk_bf16_f32 v0, v0, v2
	ds_write_b32 v148, v0 offset:5632
	v_mul_f32_e32 v0, v14, v78
	v_mul_f32_e32 v2, v15, v79
	v_cvt_pk_bf16_f32 v0, v0, v2
	ds_write_b32 v148, v0 offset:7680
	v_mul_f32_e32 v0, v32, v80
	v_mul_f32_e32 v2, v33, v81
	v_cvt_pk_bf16_f32 v0, v0, v2
	ds_write_b32 v148, v0 offset:5888
	v_mul_f32_e32 v0, v16, v80
	v_mul_f32_e32 v2, v17, v81
	v_cvt_pk_bf16_f32 v0, v0, v2
	ds_write_b32 v148, v0 offset:7936
	v_lshl_add_u32 v0, v143, 2, 0
	v_add_u32_e32 v0, 0x24000, v0
	ds_read_b32 v154, v0
	s_lshl_b32 s6, 2, s6
	s_add_i32 s6, s6, -1
	s_cmp_lg_u64 s[18:19], 0
	s_cselect_b64 s[36:37], -1, 0
	s_waitcnt lgkmcnt(0)
	ds_swizzle_b32 v0, v154 offset:swizzle(SWAP,1)
	s_ff1_i32_b64 s61, s[18:19]
	v_mov_b32_e32 v156, 0
	v_mov_b32_e32 v131, v1
	s_mov_b64 s[38:39], 0
	s_waitcnt lgkmcnt(0)
	v_or_b32_e32 v0, v0, v154
	ds_swizzle_b32 v2, v0 offset:swizzle(SWAP,2)
	v_or_b32_e32 v150, s54, v143
	v_mov_b32_e32 v68, 0
	v_mov_b32_e32 v3, v156
	v_mov_b32_e32 v4, v156
	s_waitcnt lgkmcnt(0)
	v_or_b32_e32 v0, v0, v2
	ds_swizzle_b32 v2, v0 offset:swizzle(SWAP,4)
	v_mov_b32_e32 v5, v156
	v_mov_b32_e32 v6, v156
	v_mov_b32_e32 v7, v156
	v_mov_b32_e32 v8, v156
	s_waitcnt lgkmcnt(0)
	v_or_b32_e32 v0, v0, v2
	ds_swizzle_b32 v2, v0 offset:swizzle(SWAP,8)
	v_mov_b32_e32 v9, v156
	v_mov_b32_e32 v10, v156
	v_mov_b32_e32 v11, v156
	v_mov_b32_e32 v12, v156
	s_waitcnt lgkmcnt(0)
	v_or_b32_e32 v0, v0, v2
	ds_swizzle_b32 v2, v0 offset:swizzle(SWAP,16)
	v_mov_b32_e32 v13, v156
	v_mov_b32_e32 v14, v156
	v_mov_b32_e32 v15, v156
	v_mov_b32_e32 v16, v156
	s_waitcnt lgkmcnt(0)
	v_or_b32_e32 v0, v0, v2
	v_and_or_b32 v130, v0, s6, 1
	s_and_b64 s[6:7], s[36:37], exec
	s_cselect_b32 s20, s61, -1
	s_cmp_gt_i32 s20, -1
	s_cselect_b64 s[40:41], -1, 0
	s_lshl_b64 s[6:7], s[20:21], 14
	s_add_u32 s8, s55, s6
	s_addc_u32 s9, s57, s7
	s_add_u32 s42, s58, s6
	s_mul_i32 s6, s3, 0x4a0
	s_addc_u32 s43, s59, s7
	s_add_i32 s6, s6, 0
	s_add_i32 s6, s6, 0x11880
	s_or_b32 s60, s54, 31
	s_sub_i32 s54, s54, 63
	v_lshl_add_u64 v[132:133], s[8:9], 0, v[172:173]
	v_lshl_add_u64 v[134:135], s[8:9], 0, v[176:177]
	v_add_u32_e32 v152, s6, v180
	v_mov_b32_e32 v2, 0
	v_mov_b32_e32 v17, v156
	v_mov_b32_e32 v18, 0
	v_mov_b32_e32 v19, v156
	v_mov_b32_e32 v20, v156
	v_mov_b32_e32 v21, v156
	v_mov_b32_e32 v22, v156
	v_mov_b32_e32 v23, v156
	v_mov_b32_e32 v24, v156
	v_mov_b32_e32 v25, v156
	v_mov_b32_e32 v26, v156
	v_mov_b32_e32 v27, v156
	v_mov_b32_e32 v28, v156
	v_mov_b32_e32 v29, v156
	v_mov_b32_e32 v30, v156
	v_mov_b32_e32 v31, v156
	v_mov_b32_e32 v32, v156
	v_mov_b32_e32 v33, v156
	v_mov_b32_e32 v34, 0
	v_mov_b32_e32 v35, v156
	v_mov_b32_e32 v36, v156
	v_mov_b32_e32 v37, v156
	v_mov_b32_e32 v38, v156
	v_mov_b32_e32 v39, v156
	v_mov_b32_e32 v40, v156
	v_mov_b32_e32 v41, v156
	v_mov_b32_e32 v42, v156
	v_mov_b32_e32 v43, v156
	v_mov_b32_e32 v44, v156
	v_mov_b32_e32 v45, v156
	v_mov_b32_e32 v46, v156
	v_mov_b32_e32 v47, v156
	v_mov_b32_e32 v48, v156
	v_mov_b32_e32 v49, v156
	v_mov_b32_e32 v50, 0
	v_mov_b32_e32 v51, v156
	v_mov_b32_e32 v52, v156
	v_mov_b32_e32 v53, v156
	v_mov_b32_e32 v54, v156
	v_mov_b32_e32 v55, v156
	v_mov_b32_e32 v56, v156
	v_mov_b32_e32 v57, v156
	v_mov_b32_e32 v58, v156
	v_mov_b32_e32 v59, v156
	v_mov_b32_e32 v60, v156
	v_mov_b32_e32 v61, v156
	v_mov_b32_e32 v62, v156
	v_mov_b32_e32 v63, v156
	v_mov_b32_e32 v64, v156
	v_mov_b32_e32 v65, v156
	v_readfirstlane_b32 s101, v130
	s_branch .LBB0_1975

.LBB0_1975:
	v_readfirstlane_b32 s100, v68
	s_mov_b32 s8, s101
	s_mov_b32 s9, 0
	s_add_i32 s12, s100, 1
	s_lshr_b64 s[8:9], s[8:9], s12
	s_ff1_i32_b32 s13, s8
	s_add_i32 s12, s12, s13
	s_cmp_eq_u32 s8, 0
	s_cselect_b32 s100, -1, s12
	s_cselect_b64 s[6:7], exec, 0
	v_mov_b32_e32 v157, s12
	s_waitcnt vmcnt(0)
	s_mov_b64 s[8:9], 0
	s_barrier
	s_lshl_b32 s12, s53, 14
	s_xor_b32 s12, s12, 0x4000
	s_add_i32 s13, s47, s12
	s_cmp_lt_i32 s100, 0
	s_cbranch_scc1 .Lsd_nb
	s_lshl_b32 s100, s100, 14
	s_add_u32 s8, s14, s100
	s_addc_u32 s9, s15, 0
	s_add_u32 s10, s16, s100
	s_addc_u32 s11, s17, 0
	s_add_i32 m0, s13, 0x8000
	s_nop 0
	global_load_lds_dwordx4 v172, s[8:9]
	s_add_i32 m0, s13, 0x8400
	s_nop 0
	global_load_lds_dwordx4 v176, s[8:9]
	s_branch .Lsd_v
